# XCD-locality task remap extended to phases E (GLU tiles, ssd_p3 heads), C (ssd_p1 heads) and B (s5p1 groups)
# speedup vs baseline: 1.0186x; 1.0078x over previous
.LBB0_174:
	s_sub_i32 s98, s20, s19
	s_cmp_lt_i32 s98, 0
	s_cbranch_scc1 .Lremap_e_done
	s_cmpk_lt_i32 s98, 0x220
	s_cbranch_scc0 .Lremap_e_p3
	s_and_b32 s99, s98, 7
	s_lshr_b32 s98, s98, 3
	s_lshl_b32 s99, s99, 2
	s_and_b32 s20, s98, 3
	s_add_i32 s99, s99, s20
	s_lshr_b32 s98, s98, 2
	s_lshl_b32 s98, s98, 5
	s_add_i32 s98, s98, s99
	s_add_i32 s20, s19, s98
	s_addk_i32 s20, 0x880
	s_branch .Lremap_e_done
.Lremap_e_p3:
	s_addk_i32 s98, 0xfde0
	s_and_b32 s99, s98, 7
	s_lshr_b32 s98, s98, 3
	s_mul_i32 s99, s99, 34
	s_lshr_b32 s20, s98, 3
	s_add_i32 s99, s99, s20
	s_and_b32 s98, s98, 7
	s_and_b32 s20, s99, 1
	s_lshl_b32 s20, s20, 3
	s_add_i32 s98, s98, s20
	s_lshr_b32 s99, s99, 1
	s_lshl_b32 s99, s99, 4
	s_add_i32 s98, s98, s99
	s_add_i32 s20, s19, s98

.LBB0_410:
	s_cmpk_lt_i32 s2, 0x40
	s_cbranch_scc1 .Lcloc_done
	s_cmpk_ge_i32 s2, 0x8c0
	s_cbranch_scc1 .Lcloc_done
	s_addk_i32 s2, 0xffc0
	s_and_b32 s98, s2, 7
	s_lshr_b32 s99, s2, 3
	s_mul_i32 s98, s98, 34
	s_lshr_b32 s0, s99, 3
	s_add_i32 s98, s98, s0
	s_and_b32 s99, s99, 7
	s_and_b32 s0, s98, 1
	s_lshl_b32 s0, s0, 3
	s_add_i32 s99, s99, s0
	s_lshr_b32 s98, s98, 1
	s_lshl_b32 s98, s98, 4
	s_add_i32 s2, s99, s98
	s_addk_i32 s2, 0x40

.LBB0_535:
	s_and_b64 vcc, exec, s[0:1]
	s_cbranch_vccz .LBB0_539
	s_add_i32 s88, s88, 0xf800
	s_and_b32 s98, s88, 7
	s_bfe_u32 s99, s88, 0xd0003
	s_mul_i32 s98, s98, 68
	s_add_i32 s88, s98, s99
	s_sext_i32_i16 s0, s88
	s_mulk_i32 s0, 0x7879
	s_lshr_b32 s1, s0, 31
	s_ashr_i32 s0, s0, 19
	s_add_i32 s2, s0, s1
	v_mov_b32_e32 v1, v0
	s_mul_i32 s0, s2, 17
	s_sub_i32 s3, s88, s0
	s_waitcnt vmcnt(0)
	v_and_b32_e32 v2, 0xffffffcf, v1
	v_and_b32_e32 v85, 15, v1
	v_ashrrev_i32_e32 v3, 31, v2
	s_sext_i32_i16 s4, s3
	v_lshlrev_b64 v[4:5], 9, v[2:3]
	v_lshlrev_b32_e32 v3, 4, v85
	v_lshl_or_b32 v8, s4, 10, v3
	v_or_b32_e32 v10, 0x300, v8
	v_ashrrev_i32_e32 v11, 31, v10
	v_lshlrev_b64 v[10:11], 5, v[10:11]
	s_sext_i32_i16 s5, s2
	v_mov_b32_e32 v3, 0x88000
	s_bfe_i64 s[0:1], s[2:3], 0x100000
	v_mad_i64_i32 v[10:11], s[2:3], s5, v3, v[10:11]
	v_and_b32_e32 v12, 48, v1
	v_or_b32_e32 v10, v10, v12
	v_lshl_add_u64 v[66:67], s[86:87], 0, v[10:11]
	v_or_b32_e32 v10, 0x200, v8
	v_ashrrev_i32_e32 v11, 31, v10
	v_lshlrev_b64 v[10:11], 5, v[10:11]
	v_mad_i64_i32 v[10:11], s[2:3], s5, v3, v[10:11]
	s_lshl_b64 s[6:7], s[0:1], 17
	v_or_b32_e32 v10, v10, v12
	v_lshl_add_u64 v[68:69], s[86:87], 0, v[10:11]
	v_or_b32_e32 v10, 0x100, v8
	v_lshl_add_u64 v[4:5], s[6:7], 0, v[4:5]
	v_ashrrev_i32_e32 v11, 31, v10
	v_ashrrev_i32_e32 v9, 31, v8
	v_or_b32_e32 v4, v4, v12
	v_lshlrev_b64 v[10:11], 5, v[10:11]
	v_lshlrev_b64 v[8:9], 5, v[8:9]
	v_lshl_add_u64 v[74:75], s[86:87], 0, v[4:5]
	v_or_b32_e32 v4, 16, v2
	v_or_b32_e32 v2, 32, v2
	v_mad_i64_i32 v[10:11], s[2:3], s5, v3, v[10:11]
	v_mad_i64_i32 v[8:9], s[2:3], s5, v3, v[8:9]
	v_ashrrev_i32_e32 v3, 31, v2
	v_or_b32_e32 v6, 48, v1
	v_lshlrev_b64 v[2:3], 9, v[2:3]
	v_ashrrev_i32_e32 v7, 31, v6
	v_lshl_add_u64 v[2:3], s[6:7], 0, v[2:3]
	v_lshlrev_b64 v[6:7], 9, v[6:7]
	v_ashrrev_i32_e32 v5, 31, v4
	v_or_b32_e32 v2, v2, v12
	v_lshlrev_b64 v[4:5], 9, v[4:5]
	v_lshl_add_u64 v[78:79], s[86:87], 0, v[2:3]
	v_lshl_add_u64 v[2:3], s[6:7], 0, v[6:7]
	v_lshl_add_u64 v[4:5], s[6:7], 0, v[4:5]
	v_or_b32_e32 v2, v2, v12
	v_or_b32_e32 v10, v10, v12
	v_or_b32_e32 v8, v8, v12
	v_or_b32_e32 v4, v4, v12
	v_lshl_add_u64 v[80:81], s[86:87], 0, v[2:3]
	v_mov_b32_e32 v2, 0
	v_lshrrev_b32_e32 v84, 4, v1
	v_lshl_add_u64 v[70:71], s[86:87], 0, v[10:11]
	v_lshl_add_u64 v[72:73], s[86:87], 0, v[8:9]
	v_lshl_add_u64 v[76:77], s[86:87], 0, v[4:5]
	s_mul_i32 s64, s5, 0x88000
	s_lshl_b32 s65, s4, 15
	s_add_u32 s64, s64, s65
	s_add_u32 s62, s86, s64
	s_addc_u32 s63, s87, 0
	s_add_u32 s62, s62, 0x2bf1100
	s_addc_u32 s63, s63, 0
	v_lshlrev_b32_e32 v230, 4, v1
	v_lshrrev_b32_e32 v229, 5, v1
	v_mul_u32_u24_e32 v229, 0x210, v229
	v_and_b32_e32 v231, 31, v1
	v_lshl_add_u32 v229, v231, 4, v229
	v_and_b32_e32 v228, 15, v1
	v_mul_u32_u24_e32 v228, 0x210, v228
	v_bfe_u32 v231, v1, 4, 2
	v_lshl_add_u32 v228, v231, 4, v228
	global_load_dwordx4 v[14:17], v230, s[62:63] nt
	v_add_u32_e32 v230, 0x1000, v230
	global_load_dwordx4 v[18:21], v230, s[62:63] nt
	v_add_u32_e32 v230, 0x1000, v230
	global_load_dwordx4 v[22:25], v230, s[62:63] nt
	v_add_u32_e32 v230, 0x1000, v230
	global_load_dwordx4 v[26:29], v230, s[62:63] nt
	v_add_u32_e32 v230, 0x1000, v230
	global_load_dwordx4 v[30:33], v230, s[62:63] nt
	v_add_u32_e32 v230, 0x1000, v230
	global_load_dwordx4 v[34:37], v230, s[62:63] nt
	v_add_u32_e32 v230, 0x1000, v230
	global_load_dwordx4 v[38:41], v230, s[62:63] nt
	v_add_u32_e32 v230, 0x1000, v230
	global_load_dwordx4 v[42:45], v230, s[62:63] nt
	s_waitcnt vmcnt(0)
	ds_write_b128 v229, v[14:17]
	ds_write_b128 v229, v[18:21] offset:4224
	ds_write_b128 v229, v[22:25] offset:8448
	ds_write_b128 v229, v[26:29] offset:12672
	ds_write_b128 v229, v[30:33] offset:16896
	ds_write_b128 v229, v[34:37] offset:21120
	ds_write_b128 v229, v[38:41] offset:25344
	ds_write_b128 v229, v[42:45] offset:29568
	s_waitcnt lgkmcnt(0)
	s_barrier
	s_mov_b64 s[2:3], 0
	v_mov_b32_e32 v3, v2
	v_mov_b32_e32 v4, v2
	v_mov_b32_e32 v5, v2
	v_mov_b32_e32 v6, v2
	v_mov_b32_e32 v7, v2
	v_mov_b32_e32 v8, v2
	v_mov_b32_e32 v9, v2
	v_mov_b32_e32 v10, v2
	v_mov_b32_e32 v11, v2
	v_mov_b32_e32 v12, v2
	v_mov_b32_e32 v13, v2
	v_mov_b32_e32 v38, v2
	v_mov_b32_e32 v39, v2
	v_mov_b32_e32 v40, v2
	v_mov_b32_e32 v41, v2
	v_mov_b32_e32 v50, v2
	v_mov_b32_e32 v51, v2
	v_mov_b32_e32 v52, v2
	v_mov_b32_e32 v53, v2
	v_mov_b32_e32 v54, v2
	v_mov_b32_e32 v55, v2
	v_mov_b32_e32 v56, v2
	v_mov_b32_e32 v57, v2
	v_mov_b32_e32 v58, v2
	v_mov_b32_e32 v59, v2
	v_mov_b32_e32 v60, v2
	v_mov_b32_e32 v61, v2
	v_mov_b32_e32 v62, v2
	v_mov_b32_e32 v63, v2
	v_mov_b32_e32 v64, v2
	v_mov_b32_e32 v65, v2
	v_mov_b32_e32 v46, v2
	v_mov_b32_e32 v47, v2
	v_mov_b32_e32 v48, v2
	v_mov_b32_e32 v49, v2
	v_mov_b32_e32 v42, v2
	v_mov_b32_e32 v43, v2
	v_mov_b32_e32 v44, v2
	v_mov_b32_e32 v45, v2
	v_mov_b32_e32 v34, v2
	v_mov_b32_e32 v35, v2
	v_mov_b32_e32 v36, v2
	v_mov_b32_e32 v37, v2
	v_mov_b32_e32 v26, v2
	v_mov_b32_e32 v27, v2
	v_mov_b32_e32 v28, v2
	v_mov_b32_e32 v29, v2
	v_mov_b32_e32 v30, v2
	v_mov_b32_e32 v31, v2
	v_mov_b32_e32 v32, v2
	v_mov_b32_e32 v33, v2
	v_mov_b32_e32 v22, v2
	v_mov_b32_e32 v23, v2
	v_mov_b32_e32 v24, v2
	v_mov_b32_e32 v25, v2
	v_mov_b32_e32 v18, v2
	v_mov_b32_e32 v19, v2
	v_mov_b32_e32 v20, v2
	v_mov_b32_e32 v21, v2
	v_mov_b32_e32 v14, v2
	v_mov_b32_e32 v15, v2
	v_mov_b32_e32 v16, v2
	v_mov_b32_e32 v17, v2
	s_mov_b32 s5, 0x9771000
	s_mov_b32 s6, 0x2bf1000
